# previous + mixer>GEMM2 barriers XCD-local too: converting workgroups write back L2 before arriving, consumers wait until all groups passed GEMM1 (13 of 14 barriers local)
# speedup vs baseline: 1.0559x; 1.0118x over previous
; __global__ void __launch_bounds__(NWAVES * 64, 2) fwd_kernel(Args args) {
;     ...
;         if (ph + 1 < args.ph_hi || rep + 1 < nrep) { if (args.ph_hi > 1000) grid.sync(); else xcd_barrier(xb); } else __syncthreads();
cvx_decided:
	s_mov_b32 s2, 0x7ffc
	s_bitcmp1_b32 s2, s10
	s_cbranch_scc0 cvx_fullbar
	s_cmp_eq_u32 s101, 1
	s_cbranch_scc0 cvx_fullbar
	v_readlane_b32 s22, v253, 12
	v_readlane_b32 s23, v253, 13
	v_mov_b32_e32 v3, 0
	v_mov_b32_e32 v0, 1
	s_and_b32 s2, s89, 7
	s_lshl_b32 s2, s2, 7
	s_add_i32 s2, s2, 0x3600
	s_add_u32 s22, s22, s2
	s_addc_u32 s23, s23, 0
	s_cmpk_lt_u32 s89, 0x80
	s_cbranch_scc1 cvx_nowb
	s_cmp_eq_u32 s10, 2
	s_cbranch_scc1 cvx_wb
	s_cmp_eq_u32 s10, 9
	s_cbranch_scc0 cvx_nowb
cvx_wb:
	buffer_wbl2 sc1
	s_waitcnt vmcnt(0)
cvx_nowb:
	global_atomic_add v1, v3, v0, s[22:23] sc0
	s_waitcnt vmcnt(0)
	v_readfirstlane_b32 s2, v1
	s_nop 0
	s_lshr_b32 s3, s2, 5
	s_add_i32 s3, s3, 1
	s_lshl_b32 s3, s3, 5
	s_mov_b32 s2, 0

; __global__ void __launch_bounds__(NWAVES * 64, 2) fwd_kernel(Args args) {
;     ...
;         if (ph + 1 < args.ph_hi || rep + 1 < nrep) { if (args.ph_hi > 1000) grid.sync(); else xcd_barrier(xb); } else __syncthreads();
cvx_arrived:
	s_and_b32 s2, s89, 7
	s_mov_b32 s35, 1
	s_cmp_eq_u32 s10, 8
	s_cbranch_scc1 cvx_w71
	s_movk_i32 s3, 32
	s_cmp_eq_u32 s10, 3
	s_cbranch_scc1 cvx_wall
	s_movk_i32 s3, 256
	s_cmp_eq_u32 s10, 10
	s_cbranch_scc1 cvx_wall
	s_cmp_eq_u32 s10, 5
	s_cbranch_scc1 cvx_w45a
	s_cmp_eq_u32 s10, 12
	s_cbranch_scc1 cvx_w45b
	s_cmp_eq_u32 s10, 14
	s_cbranch_scc1 cvx_w67
	s_branch cvx_done
cvx_w45a:
	s_movk_i32 s3, 96
	s_branch cvx_w45
cvx_w45b:
	s_movk_i32 s3, 320

; __global__ void __launch_bounds__(NWAVES * 64, 2) fwd_kernel(Args args) {
;     ...
;         if (ph + 1 < args.ph_hi || rep + 1 < nrep) { if (args.ph_hi > 1000) grid.sync(); else xcd_barrier(xb); } else __syncthreads();
cvx_w71:
	s_cmp_eq_u32 s2, 7
	s_cbranch_scc1 cvx_done
	s_movk_i32 s3, 224
	s_add_u32 s22, s22, 0x80
	s_addc_u32 s23, s23, 0
	s_branch cvx_waitn
cvx_w67:
	s_cmp_gt_u32 s2, 3
	s_cbranch_scc1 cvx_done
	s_movk_i32 s3, 352
	s_mov_b32 s35, 2
	s_lshl_b32 s2, s2, 7
	s_add_u32 s22, s22, s2
	s_addc_u32 s23, s23, 0

; __global__ void __launch_bounds__(NWAVES * 64, 2) fwd_kernel(Args args) {
;     ...
;         if (ph + 1 < args.ph_hi || rep + 1 < nrep) { if (args.ph_hi > 1000) grid.sync(); else xcd_barrier(xb); } else __syncthreads();
cvx_wall:
	v_readlane_b32 s22, v253, 12
	v_readlane_b32 s23, v253, 13
	s_mov_b32 s2, 0
	s_add_u32 s22, s22, 0x3600
	s_addc_u32 s23, s23, 0
cvx_wall_spin:
	global_load_dword v4, v3, s[22:23] offset:0 sc1
	global_load_dword v5, v3, s[22:23] offset:128 sc1
	global_load_dword v6, v3, s[22:23] offset:256 sc1
	global_load_dword v7, v3, s[22:23] offset:384 sc1
	global_load_dword v8, v3, s[22:23] offset:512 sc1
	global_load_dword v9, v3, s[22:23] offset:640 sc1
	global_load_dword v10, v3, s[22:23] offset:768 sc1
	global_load_dword v11, v3, s[22:23] offset:896 sc1
	s_waitcnt vmcnt(0)
	v_min_u32_e32 v4, v4, v5
	v_min_u32_e32 v6, v6, v7
	v_min_u32_e32 v8, v8, v9
	v_min_u32_e32 v10, v10, v11
	v_min_u32_e32 v4, v4, v6
	v_min_u32_e32 v8, v8, v10
	v_min_u32_e32 v4, v4, v8
	v_readfirstlane_b32 s34, v4
	s_nop 0
	s_cmp_ge_u32 s34, s3
	s_cbranch_scc1 cvx_done
	s_sleep 1
	s_add_i32 s2, s2, 1
	s_cmp_lt_u32 s2, 0x100000
	s_cbranch_scc1 cvx_wall_spin
